# static priority scope: waves 0-3 raised in the GEMM and other phases, but priority reset to 0 for all waves inside attention units (restored at unit end)
# baseline (speedup 1.0000x reference)
.LBB0_1335:
	s_setprio 0
	v_mov_b32_e32 v36, v204
	s_nop 0
	v_readfirstlane_b32 s28, v36
	s_ashr_i32 s55, s28, 6
	s_lshl_b32 s44, s55, 5
	s_ashr_i32 s45, s44, 31
	v_and_b32_e32 v224, 63, v36
	s_lshl_b64 s[8:9], s[44:45], 10
	s_add_u32 s8, s38, s8
	v_lshlrev_b32_e32 v0, 10, v224
	s_addc_u32 s9, s39, s9
	v_lshl_add_u64 v[2:3], s[46:47], 0, v[0:1]
	s_lshl_b32 s10, s55, 3
	s_lshl_b32 s5, s55, 4
	v_bfe_u32 v0, v36, 2, 4
	s_ashr_i32 s11, s10, 31
	v_and_or_b32 v0, s5, 48, v0
	s_ashr_i32 s5, s28, 3
	v_lshl_add_u64 v[176:177], s[10:11], 1, v[2:3]
	s_and_b32 s10, s5, 0xffffffe0
	s_ashr_i32 s11, s10, 31
	s_lshl_b32 s38, s55, 10
	v_lshlrev_b32_e32 v0, 10, v0
	v_lshlrev_b32_e32 v225, 3, v36
	s_cmp_lg_u32 0, -1
	v_lshl_add_u64 v[2:3], s[48:49], 0, v[0:1]
	v_and_b32_e32 v228, 24, v225
	s_cselect_b32 s5, 0, 0
	v_bfe_u32 v227, v36, 5, 1
	v_lshl_add_u64 v[2:3], s[10:11], 1, v[2:3]
	v_lshlrev_b32_e32 v0, 1, v228
	s_add_i32 s5, s38, s5
	s_mov_b32 s10, m0
	s_mov_b32 m0, s5
	s_nop 0
	global_load_lds_dwordx4 v[176:177], off
	s_mov_b32 m0, s10
	v_and_b32_e32 v226, 31, v36
	v_lshl_add_u64 v[34:35], v[2:3], 0, v[0:1]
	s_add_i32 s56, s5, 0x6000
	s_mov_b32 s10, m0
	s_mov_b32 m0, s56
	s_nop 0
	global_load_lds_dwordx4 v[34:35], off
	s_mov_b32 m0, s10
	v_lshl_add_u64 v[2:3], v[176:177], 0, s[16:17]
	v_lshlrev_b32_e32 v5, 4, v227
	s_add_i32 s10, s5, 0x2000
	s_mov_b32 s11, m0
	s_mov_b32 m0, s10
	s_nop 0
	global_load_lds_dwordx4 v[2:3], off
	s_mov_b32 m0, s11
	v_lshl_or_b32 v2, v226, 10, v5
	global_load_dwordx4 v[124:127], v2, s[8:9]
	global_load_dwordx4 v[120:123], v2, s[8:9] offset:32
	global_load_dwordx4 v[116:119], v2, s[8:9] offset:64
	global_load_dwordx4 v[112:115], v2, s[8:9] offset:96
	v_lshlrev_b32_e32 v0, 10, v227
	v_lshlrev_b32_e32 v4, 4, v226
	v_add3_u32 v235, 0, v0, v4
	v_lshl_add_u64 v[2:3], v[176:177], 0, s[30:31]
	s_add_i32 s8, s5, 0x4000
	s_mov_b32 s9, m0
	s_mov_b32 m0, s8
	s_nop 0
	global_load_lds_dwordx4 v[2:3], off
	s_mov_b32 m0, s9
	v_add_u32_e32 v0, 0, v5
	s_waitcnt vmcnt(3) lgkmcnt(0)
	s_barrier
	v_add_u32_e32 v0, 0x15000, v0
	ds_read_b128 v[2:5], v0
	ds_read_b128 v[6:9], v0 offset:32
	ds_read_b128 v[10:13], v0 offset:128
	v_lshlrev_b32_e32 v229, 2, v227
	v_or_b32_e32 v234, s44, v226
	s_waitcnt lgkmcnt(2)
	v_xor_b32_e32 v5, 0x80000000, v5
	v_xor_b32_e32 v4, 0x80000000, v4
	s_waitcnt lgkmcnt(0)
	v_xor_b32_e32 v21, 0x80000000, v13
	v_xor_b32_e32 v20, 0x80000000, v12
	v_xor_b32_e32 v19, 0x80000000, v11
	v_xor_b32_e32 v18, 0x80000000, v10
	ds_read_b128 v[10:13], v0 offset:160
	v_xor_b32_e32 v3, 0x80000000, v3
	v_xor_b32_e32 v2, 0x80000000, v2
	v_xor_b32_e32 v6, 0x80000000, v6
	v_xor_b32_e32 v7, 0x80000000, v7
	s_waitcnt lgkmcnt(0)
	v_xor_b32_e32 v22, 0x80000000, v10
	v_xor_b32_e32 v23, 0x80000000, v11
	v_xor_b32_e32 v24, 0x80000000, v12
	v_xor_b32_e32 v25, 0x80000000, v13
	ds_read_b128 v[10:13], v0 offset:64
	ds_read_b128 v[14:17], v0 offset:192
	v_xor_b32_e32 v8, 0x80000000, v8
	v_xor_b32_e32 v9, 0x80000000, v9
	s_cmp_gt_u32 s4, 4
	s_waitcnt lgkmcnt(1)
	v_xor_b32_e32 v10, 0x80000000, v10
	s_waitcnt lgkmcnt(0)
	v_xor_b32_e32 v26, 0x80000000, v14
	v_xor_b32_e32 v27, 0x80000000, v15
	v_xor_b32_e32 v28, 0x80000000, v16
	v_xor_b32_e32 v29, 0x80000000, v17
	ds_read_b128 v[14:17], v0 offset:96
	ds_read_b128 v[30:33], v0 offset:224
	ds_read_b128 v[38:41], v235
	ds_read_b128 v[42:45], v235 offset:512
	v_xor_b32_e32 v11, 0x80000000, v11
	v_xor_b32_e32 v12, 0x80000000, v12
	v_xor_b32_e32 v13, 0x80000000, v13
	s_waitcnt lgkmcnt(3)
	v_xor_b32_e32 v14, 0x80000000, v14
	v_xor_b32_e32 v15, 0x80000000, v15
	v_xor_b32_e32 v16, 0x80000000, v16
	v_xor_b32_e32 v17, 0x80000000, v17
	s_waitcnt lgkmcnt(2)
	v_xor_b32_e32 v30, 0x80000000, v30
	v_xor_b32_e32 v31, 0x80000000, v31
	v_xor_b32_e32 v32, 0x80000000, v32
	v_xor_b32_e32 v33, 0x80000000, v33
	s_waitcnt vmcnt(3) lgkmcnt(1)
	v_mfma_f32_32x32x16_bf16 v[2:17], v[38:41], v[124:127], v[2:17]
	s_waitcnt lgkmcnt(0)
	v_mfma_f32_32x32x16_bf16 v[18:33], v[42:45], v[124:127], v[18:33]
	ds_read_b128 v[38:41], v235 offset:2048
	ds_read_b128 v[42:45], v235 offset:2560
	s_waitcnt vmcnt(2) lgkmcnt(1)
	v_mfma_f32_32x32x16_bf16 v[2:17], v[38:41], v[120:123], v[2:17]
	s_waitcnt lgkmcnt(0)
	v_mfma_f32_32x32x16_bf16 v[18:33], v[42:45], v[120:123], v[18:33]
	ds_read_b128 v[38:41], v235 offset:4096
	ds_read_b128 v[42:45], v235 offset:4608
	s_waitcnt vmcnt(1) lgkmcnt(1)
	v_mfma_f32_32x32x16_bf16 v[2:17], v[38:41], v[116:119], v[2:17]
	s_waitcnt lgkmcnt(0)
	v_mfma_f32_32x32x16_bf16 v[18:33], v[42:45], v[116:119], v[18:33]
	ds_read_b128 v[38:41], v235 offset:6144
	ds_read_b128 v[42:45], v235 offset:6656
	s_waitcnt vmcnt(0) lgkmcnt(1)
	v_mfma_f32_32x32x16_bf16 v[2:17], v[38:41], v[112:115], v[2:17]
	s_waitcnt lgkmcnt(0)
	v_mfma_f32_32x32x16_bf16 v[18:33], v[42:45], v[112:115], v[18:33]
	s_nop 15
	s_nop 7
	s_cbranch_scc1 .LBB0_1337
	v_or_b32_e32 v0, 32, v229
	v_cmp_le_i32_e32 vcc, v0, v234
	v_or_b32_e32 v0, 33, v229
	s_nop 7
	v_cndmask_b32_e32 v18, v223, v18, vcc
	v_cmp_lt_i32_e32 vcc, v229, v234
	s_nop 1
	v_cndmask_b32_e32 v3, v223, v3, vcc
	v_cmp_le_i32_e32 vcc, v229, v234
	s_nop 1
	v_cndmask_b32_e32 v2, v223, v2, vcc
	v_cmp_le_i32_e32 vcc, v0, v234
	v_or_b32_e32 v0, 2, v229
	s_nop 0
	v_cndmask_b32_e32 v19, v223, v19, vcc
	v_cmp_le_i32_e32 vcc, v0, v234
	v_or_b32_e32 v0, 34, v229
	s_nop 0
	v_cndmask_b32_e32 v4, v223, v4, vcc
	v_cmp_le_i32_e32 vcc, v0, v234
	v_or_b32_e32 v0, 3, v229
	s_nop 0
	v_cndmask_b32_e32 v20, v223, v20, vcc
	v_cmp_le_i32_e32 vcc, v0, v234
	v_or_b32_e32 v0, 35, v229
	s_nop 0
	v_cndmask_b32_e32 v5, v223, v5, vcc
	v_cmp_le_i32_e32 vcc, v0, v234
	v_or_b32_e32 v0, 8, v229
	s_nop 0
	v_cndmask_b32_e32 v21, v223, v21, vcc
	v_cmp_le_i32_e32 vcc, v0, v234
	v_or_b32_e32 v0, 40, v229
	s_nop 0
	v_cndmask_b32_e32 v6, v223, v6, vcc
	v_cmp_le_i32_e32 vcc, v0, v234
	v_or_b32_e32 v0, 9, v229
	s_nop 0
	v_cndmask_b32_e32 v22, v223, v22, vcc
	v_cmp_le_i32_e32 vcc, v0, v234
	v_or_b32_e32 v0, 41, v229
	s_nop 0
	v_cndmask_b32_e32 v7, v223, v7, vcc
	v_cmp_le_i32_e32 vcc, v0, v234
	v_or_b32_e32 v0, 10, v229
	s_nop 0
	v_cndmask_b32_e32 v23, v223, v23, vcc
	v_cmp_le_i32_e32 vcc, v0, v234
	v_or_b32_e32 v0, 42, v229
	s_nop 0
	v_cndmask_b32_e32 v8, v223, v8, vcc
	v_cmp_le_i32_e32 vcc, v0, v234
	v_or_b32_e32 v0, 11, v229
	s_nop 0
	v_cndmask_b32_e32 v24, v223, v24, vcc
	v_cmp_le_i32_e32 vcc, v0, v234
	v_or_b32_e32 v0, 43, v229
	s_nop 0
	v_cndmask_b32_e32 v9, v223, v9, vcc
	v_cmp_le_i32_e32 vcc, v0, v234
	v_or_b32_e32 v0, 16, v229
	s_nop 0
	v_cndmask_b32_e32 v25, v223, v25, vcc
	v_cmp_le_i32_e32 vcc, v0, v234
	v_or_b32_e32 v0, 48, v229
	s_nop 0
	v_cndmask_b32_e32 v10, v223, v10, vcc
	v_cmp_le_i32_e32 vcc, v0, v234
	v_or_b32_e32 v0, 17, v229
	s_nop 0
	v_cndmask_b32_e32 v26, v223, v26, vcc
	v_cmp_le_i32_e32 vcc, v0, v234
	v_or_b32_e32 v0, 49, v229
	s_nop 0
	v_cndmask_b32_e32 v11, v223, v11, vcc
	v_cmp_le_i32_e32 vcc, v0, v234
	v_or_b32_e32 v0, 18, v229
	s_nop 0
	v_cndmask_b32_e32 v27, v223, v27, vcc
	v_cmp_le_i32_e32 vcc, v0, v234
	v_or_b32_e32 v0, 50, v229
	s_nop 0
	v_cndmask_b32_e32 v12, v223, v12, vcc
	v_cmp_le_i32_e32 vcc, v0, v234
	v_or_b32_e32 v0, 19, v229
	s_nop 0
	v_cndmask_b32_e32 v28, v223, v28, vcc
	v_cmp_le_i32_e32 vcc, v0, v234
	v_or_b32_e32 v0, 51, v229
	s_nop 0
	v_cndmask_b32_e32 v13, v223, v13, vcc
	v_cmp_le_i32_e32 vcc, v0, v234
	v_or_b32_e32 v0, 24, v229
	s_nop 0
	v_cndmask_b32_e32 v29, v223, v29, vcc
	v_cmp_le_i32_e32 vcc, v0, v234
	v_or_b32_e32 v0, 56, v229
	s_nop 0
	v_cndmask_b32_e32 v14, v223, v14, vcc
	v_cmp_le_i32_e32 vcc, v0, v234
	v_or_b32_e32 v0, 25, v229
	s_nop 0
	v_cndmask_b32_e32 v30, v223, v30, vcc
	v_cmp_le_i32_e32 vcc, v0, v234
	v_or_b32_e32 v0, 57, v229
	s_nop 0
	v_cndmask_b32_e32 v15, v223, v15, vcc
	v_cmp_le_i32_e32 vcc, v0, v234
	v_or_b32_e32 v0, 26, v229
	s_nop 0
	v_cndmask_b32_e32 v31, v223, v31, vcc
	v_cmp_le_i32_e32 vcc, v0, v234
	v_or_b32_e32 v0, 58, v229
	s_nop 0
	v_cndmask_b32_e32 v16, v223, v16, vcc
	v_cmp_le_i32_e32 vcc, v0, v234
	v_or_b32_e32 v0, 27, v229
	s_nop 0
	v_cndmask_b32_e32 v32, v223, v32, vcc
	v_cmp_le_i32_e32 vcc, v0, v234
	v_or_b32_e32 v0, 59, v229
	s_nop 0
	v_cndmask_b32_e32 v17, v223, v17, vcc
	v_cmp_le_i32_e32 vcc, v0, v234
	s_nop 1
	v_cndmask_b32_e32 v33, v223, v33, vcc

.LBB0_1369:
	v_readfirstlane_b32 s4, v204
	s_lshr_b32 s4, s4, 8
	s_cmp_eq_u32 s4, 0
	s_cbranch_scc0 .Lattn_prio_back
	s_setprio 1
